# v65 + layer-1 W_in lines touched (one dword per 128 B line) by idle waves during the last three layer-0 barrier waits
# baseline (speedup 1.0000x reference)
; __device__ __forceinline__ unsigned xb_ld(unsigned* p)              { return __hip_atomic_load(p, __ATOMIC_RELAXED, __HIP_MEMORY_SCOPE_AGENT); }
; __device__ __forceinline__ unsigned xb_add(unsigned* p, unsigned v) { return __hip_atomic_fetch_add(p, v, __ATOMIC_RELAXED, __HIP_MEMORY_SCOPE_AGENT); }
; #define XB_SPIN(cond, bar) do { unsigned _sp = 0; while (cond) { __builtin_amdgcn_s_sleep(1); \
;     if ((++_sp & 255u) == 0u) { if (xb_ld(&(bar)[XB_TMO])) break; if (_sp > XB_SPIN_CAP) { atomicAdd(&(bar)[XB_TMO], 1u); break; } } } } while (0)
; __device__ __forceinline__ void xcd_barrier(const XcdBarrier& b, bool local = false) {
;     asm volatile("s_waitcnt vmcnt(0)" ::: "memory");
;     __syncthreads();
;     if (threadIdx.x == 0) {
;         unsigned* bar = b.bar;
;         __builtin_amdgcn_s_waitcnt(0);
;         unsigned nloc = b.st[0], nx = b.st[1];
;         if (nloc == 0u) { xcd_barrier_complete(bar, b.x, nloc, nx); b.st[0] = nloc; b.st[1] = nx; }
;         const unsigned old = xb_add(&bar[XB_XSUB(b.x)], 1u);
;         const unsigned gen = old / nloc;
;         if (old + 1u == (gen + 1u) * nloc) {
;             if (!local) {
;             __builtin_amdgcn_fence(__ATOMIC_RELEASE, "agent");
;             asm volatile("s_waitcnt vmcnt(0)" ::: "memory");
;             const unsigned og = xb_add(&bar[XB_TOP], 1u);
;             const unsigned tg = og / nx;
;             if (og + 1u == (tg + 1u) * nx) xb_add(&bar[XB_TOPGEN], 1u);
;             else XB_SPIN(xb_ld(&bar[XB_TOPGEN]) == tg, bar);
;             }
;             __builtin_amdgcn_fence(__ATOMIC_ACQUIRE, "agent");
;             xb_add(&bar[XB_XGEN(b.x)], 1u);
;             asm volatile("s_waitcnt vmcnt(0)" ::: "memory");
;         } else {
;             XB_SPIN(xb_ld(&bar[XB_XGEN(b.x)]) == gen, bar);
;             __builtin_amdgcn_fence(__ATOMIC_ACQUIRE, "agent");
;             asm volatile("s_waitcnt vmcnt(0)" ::: "memory");
;         }
;     }
;     __syncthreads();
.LBB0_682:
	s_or_b64 exec, exec, s[40:41]
	s_cmp_lg_u32 s78, 0
	s_cbranch_scc1 .Lwl0_x
	v_readfirstlane_b32 s98, v188
	s_cmp_lt_u32 s98, 64
	s_cbranch_scc1 .Lwl0_x
	v_readlane_b32 vcc_lo, v251, 52
	v_readlane_b32 vcc_hi, v251, 53
	v_readlane_b32 s98, v252, 36
	v_readlane_b32 s99, v252, 37
	s_lshl_b32 vcc_lo, vcc_lo, 3
	s_add_i32 vcc_lo, vcc_lo, vcc_hi
	s_mul_i32 vcc_lo, vcc_lo, 448
	s_add_u32 s98, s98, 0x3c00000
	s_addc_u32 s99, s99, 0
	v_subrev_u32_e32 v4, 64, v188
	v_add_u32_e32 v4, vcc_lo, v4
	v_add_u32_e32 v5, 0x0, v4
	v_min_u32_e32 v5, 0x77fff, v5
	v_lshlrev_b32_e32 v5, 7, v5
	global_load_dword v255, v5, s[98:99]
	v_add_u32_e32 v5, 0x1c000, v4
	v_min_u32_e32 v5, 0x77fff, v5
	v_lshlrev_b32_e32 v5, 7, v5
	global_load_dword v255, v5, s[98:99]

; __device__ __forceinline__ unsigned xb_ld(unsigned* p)              { return __hip_atomic_load(p, __ATOMIC_RELAXED, __HIP_MEMORY_SCOPE_AGENT); }
; __device__ __forceinline__ unsigned xb_add(unsigned* p, unsigned v) { return __hip_atomic_fetch_add(p, v, __ATOMIC_RELAXED, __HIP_MEMORY_SCOPE_AGENT); }
; #define XB_SPIN(cond, bar) do { unsigned _sp = 0; while (cond) { __builtin_amdgcn_s_sleep(1); \
;     if ((++_sp & 255u) == 0u) { if (xb_ld(&(bar)[XB_TMO])) break; if (_sp > XB_SPIN_CAP) { atomicAdd(&(bar)[XB_TMO], 1u); break; } } } } while (0)
; __device__ __forceinline__ void xcd_barrier(const XcdBarrier& b, bool local = false) {
;     asm volatile("s_waitcnt vmcnt(0)" ::: "memory");
;     __syncthreads();
;     if (threadIdx.x == 0) {
;         unsigned* bar = b.bar;
;         __builtin_amdgcn_s_waitcnt(0);
;         unsigned nloc = b.st[0], nx = b.st[1];
;         if (nloc == 0u) { xcd_barrier_complete(bar, b.x, nloc, nx); b.st[0] = nloc; b.st[1] = nx; }
;         const unsigned old = xb_add(&bar[XB_XSUB(b.x)], 1u);
;         const unsigned gen = old / nloc;
;         if (old + 1u == (gen + 1u) * nloc) {
;             if (!local) {
;             __builtin_amdgcn_fence(__ATOMIC_RELEASE, "agent");
;             asm volatile("s_waitcnt vmcnt(0)" ::: "memory");
;             const unsigned og = xb_add(&bar[XB_TOP], 1u);
;             const unsigned tg = og / nx;
;             if (og + 1u == (tg + 1u) * nx) xb_add(&bar[XB_TOPGEN], 1u);
;             else XB_SPIN(xb_ld(&bar[XB_TOPGEN]) == tg, bar);
;             }
;             __builtin_amdgcn_fence(__ATOMIC_ACQUIRE, "agent");
;             xb_add(&bar[XB_XGEN(b.x)], 1u);
;             asm volatile("s_waitcnt vmcnt(0)" ::: "memory");
;         } else {
;             XB_SPIN(xb_ld(&bar[XB_XGEN(b.x)]) == gen, bar);
;             __builtin_amdgcn_fence(__ATOMIC_ACQUIRE, "agent");
;             asm volatile("s_waitcnt vmcnt(0)" ::: "memory");
;         }
;     }
;     __syncthreads();
.LBB0_771:
	s_or_b64 exec, exec, s[40:41]
	s_cmp_lg_u32 s78, 0
	s_cbranch_scc1 .Lwl1_x
	v_readfirstlane_b32 s98, v188
	s_cmp_lt_u32 s98, 64
	s_cbranch_scc1 .Lwl1_x
	v_readlane_b32 vcc_lo, v251, 52
	v_readlane_b32 vcc_hi, v251, 53
	v_readlane_b32 s98, v252, 36
	v_readlane_b32 s99, v252, 37
	s_lshl_b32 vcc_lo, vcc_lo, 3
	s_add_i32 vcc_lo, vcc_lo, vcc_hi
	s_mul_i32 vcc_lo, vcc_lo, 448
	s_add_u32 s98, s98, 0x3c00000
	s_addc_u32 s99, s99, 0
	v_subrev_u32_e32 v4, 64, v188
	v_add_u32_e32 v4, vcc_lo, v4
	v_add_u32_e32 v5, 0x38000, v4
	v_min_u32_e32 v5, 0x77fff, v5
	v_lshlrev_b32_e32 v5, 7, v5
	global_load_dword v255, v5, s[98:99]
	v_add_u32_e32 v5, 0x54000, v4
	v_min_u32_e32 v5, 0x77fff, v5
	v_lshlrev_b32_e32 v5, 7, v5
	global_load_dword v255, v5, s[98:99]

; __device__ __forceinline__ unsigned xb_ld(unsigned* p)              { return __hip_atomic_load(p, __ATOMIC_RELAXED, __HIP_MEMORY_SCOPE_AGENT); }
; __device__ __forceinline__ unsigned xb_add(unsigned* p, unsigned v) { return __hip_atomic_fetch_add(p, v, __ATOMIC_RELAXED, __HIP_MEMORY_SCOPE_AGENT); }
; #define XB_SPIN(cond, bar) do { unsigned _sp = 0; while (cond) { __builtin_amdgcn_s_sleep(1); \
;     if ((++_sp & 255u) == 0u) { if (xb_ld(&(bar)[XB_TMO])) break; if (_sp > XB_SPIN_CAP) { atomicAdd(&(bar)[XB_TMO], 1u); break; } } } } while (0)
; __device__ __forceinline__ void xcd_barrier(const XcdBarrier& b, bool local = false) {
;     asm volatile("s_waitcnt vmcnt(0)" ::: "memory");
;     __syncthreads();
;     if (threadIdx.x == 0) {
;         unsigned* bar = b.bar;
;         __builtin_amdgcn_s_waitcnt(0);
;         unsigned nloc = b.st[0], nx = b.st[1];
;         if (nloc == 0u) { xcd_barrier_complete(bar, b.x, nloc, nx); b.st[0] = nloc; b.st[1] = nx; }
;         const unsigned old = xb_add(&bar[XB_XSUB(b.x)], 1u);
;         const unsigned gen = old / nloc;
;         if (old + 1u == (gen + 1u) * nloc) {
;             if (!local) {
;             __builtin_amdgcn_fence(__ATOMIC_RELEASE, "agent");
;             asm volatile("s_waitcnt vmcnt(0)" ::: "memory");
;             const unsigned og = xb_add(&bar[XB_TOP], 1u);
;             const unsigned tg = og / nx;
;             if (og + 1u == (tg + 1u) * nx) xb_add(&bar[XB_TOPGEN], 1u);
;             else XB_SPIN(xb_ld(&bar[XB_TOPGEN]) == tg, bar);
;             }
;             __builtin_amdgcn_fence(__ATOMIC_ACQUIRE, "agent");
;             xb_add(&bar[XB_XGEN(b.x)], 1u);
;             asm volatile("s_waitcnt vmcnt(0)" ::: "memory");
;         } else {
;             XB_SPIN(xb_ld(&bar[XB_XGEN(b.x)]) == gen, bar);
;             __builtin_amdgcn_fence(__ATOMIC_ACQUIRE, "agent");
;             asm volatile("s_waitcnt vmcnt(0)" ::: "memory");
;         }
;     }
;     __syncthreads();
.LBB0_876:
	s_or_b64 exec, exec, s[40:41]
	s_cmp_lg_u32 s78, 0
	s_cbranch_scc1 .Lwl2_x
	v_readfirstlane_b32 s98, v188
	s_cmp_lt_u32 s98, 64
	s_cbranch_scc1 .Lwl2_x
	v_readlane_b32 vcc_lo, v251, 52
	v_readlane_b32 vcc_hi, v251, 53
	v_readlane_b32 s98, v252, 36
	v_readlane_b32 s99, v252, 37
	s_lshl_b32 vcc_lo, vcc_lo, 3
	s_add_i32 vcc_lo, vcc_lo, vcc_hi
	s_mul_i32 vcc_lo, vcc_lo, 448
	s_add_u32 s98, s98, 0x3c00000
	s_addc_u32 s99, s99, 0
	v_subrev_u32_e32 v4, 64, v188
	v_add_u32_e32 v4, vcc_lo, v4
	v_add_u32_e32 v5, 0x70000, v4
	v_min_u32_e32 v5, 0x77fff, v5
	v_lshlrev_b32_e32 v5, 7, v5
	global_load_dword v255, v5, s[98:99]
	v_add_u32_e32 v5, 0x8c000, v4
	v_min_u32_e32 v5, 0x77fff, v5
	v_lshlrev_b32_e32 v5, 7, v5
	global_load_dword v255, v5, s[98:99]
.Lwl2_x:
	s_mov_b64 s[4:5], 0
	s_waitcnt lgkmcnt(0)
	s_barrier
